# v17 + removed 8 provably redundant post-barrier lgkmcnt(0) waits in the GEMM K-loop and its peeled iteration
# speedup vs baseline: 1.0031x; 1.0014x over previous
.Lk_peel:
	s_add_i32 s44, s14, 2
	s_add_u32 s45, s0, 0x80
	s_addc_u32 s15, s1, 0
	s_add_i32 s57, 0, 0x10000
	s_cmp_eq_u32 s18, s14
	s_cselect_b32 s15, s89, s15
	s_cselect_b32 s14, s88, s45
	s_cselect_b32 vcc_hi, s11, s43
	s_cselect_b32 vcc_lo, s10, s42
	s_add_i32 s45, 0, 0x14000
	s_waitcnt lgkmcnt(0)
	ds_read_b128 v[130:133], v248
	ds_read_b128 v[134:137], v248 offset:1024
	ds_read_b128 v[138:141], v248 offset:2048
	ds_read_b128 v[142:145], v248 offset:3072
	ds_read_b128 v[146:149], v248 offset:16384
	ds_read_b128 v[150:153], v248 offset:17408
	ds_read_b128 v[154:157], v248 offset:18432
	ds_read_b128 v[158:161], v248 offset:19456
	s_add_i32 m0, s70, 0xc000
	ds_read_b128 v[162:165], v237
	ds_read_b128 v[166:169], v237 offset:1024
	ds_read_b128 v[184:187], v237 offset:2048
	ds_read_b128 v[188:191], v237 offset:3072
	ds_read_b128 v[192:195], v237 offset:4096
	ds_read_b128 v[196:199], v237 offset:5120
	ds_read_b128 v[200:203], v237 offset:6144
	ds_read_b128 v[214:217], v237 offset:7168
	global_load_lds_dwordx4 v180, s[0:1]
	s_add_i32 m0, s70, 0xe000
	s_nop 0
	global_load_lds_dwordx4 v182, s[0:1]
	s_waitcnt vmcnt(8)
	s_waitcnt lgkmcnt(0)
	s_barrier
	s_setprio 1
	v_mfma_f32_16x16x32_bf16 v[122:125], v[130:133], v[162:165], 0
	v_mfma_f32_16x16x32_bf16 v[126:129], v[138:141], v[162:165], 0
	v_mfma_f32_16x16x32_bf16 v[106:109], v[130:133], v[184:187], 0
	v_mfma_f32_16x16x32_bf16 v[110:113], v[138:141], v[184:187], 0
	v_mfma_f32_16x16x32_bf16 v[90:93], v[130:133], v[192:195], 0
	v_mfma_f32_16x16x32_bf16 v[94:97], v[138:141], v[192:195], 0
	v_mfma_f32_16x16x32_bf16 v[74:77], v[130:133], v[200:203], 0
	v_mfma_f32_16x16x32_bf16 v[78:81], v[138:141], v[200:203], 0
	v_mfma_f32_16x16x32_bf16 v[122:125], v[134:137], v[166:169], v[122:125]
	v_mfma_f32_16x16x32_bf16 v[126:129], v[142:145], v[166:169], v[126:129]
	v_mfma_f32_16x16x32_bf16 v[106:109], v[134:137], v[188:191], v[106:109]
	v_mfma_f32_16x16x32_bf16 v[110:113], v[142:145], v[188:191], v[110:113]
	v_mfma_f32_16x16x32_bf16 v[90:93], v[134:137], v[196:199], v[90:93]
	v_mfma_f32_16x16x32_bf16 v[94:97], v[142:145], v[196:199], v[94:97]
	v_mfma_f32_16x16x32_bf16 v[74:77], v[134:137], v[214:217], v[74:77]
	v_mfma_f32_16x16x32_bf16 v[78:81], v[142:145], v[214:217], v[78:81]
	v_mfma_f32_16x16x32_bf16 v[114:117], v[146:149], v[162:165], 0
	v_mfma_f32_16x16x32_bf16 v[118:121], v[154:157], v[162:165], 0
	v_mfma_f32_16x16x32_bf16 v[98:101], v[146:149], v[184:187], 0
	v_mfma_f32_16x16x32_bf16 v[102:105], v[154:157], v[184:187], 0
	v_mfma_f32_16x16x32_bf16 v[82:85], v[146:149], v[192:195], 0
	v_mfma_f32_16x16x32_bf16 v[86:89], v[154:157], v[192:195], 0
	v_mfma_f32_16x16x32_bf16 v[66:69], v[146:149], v[200:203], 0
	v_mfma_f32_16x16x32_bf16 v[70:73], v[154:157], v[200:203], 0
	v_mfma_f32_16x16x32_bf16 v[114:117], v[150:153], v[166:169], v[114:117]
	v_mfma_f32_16x16x32_bf16 v[118:121], v[158:161], v[166:169], v[118:121]
	v_mfma_f32_16x16x32_bf16 v[98:101], v[150:153], v[188:191], v[98:101]
	v_mfma_f32_16x16x32_bf16 v[102:105], v[158:161], v[188:191], v[102:105]
	v_mfma_f32_16x16x32_bf16 v[82:85], v[150:153], v[196:199], v[82:85]
	v_mfma_f32_16x16x32_bf16 v[86:89], v[158:161], v[196:199], v[86:89]
	v_mfma_f32_16x16x32_bf16 v[66:69], v[150:153], v[214:217], v[66:69]
	v_mfma_f32_16x16x32_bf16 v[70:73], v[158:161], v[214:217], v[70:73]
	s_setprio 0
	s_barrier
	s_add_i32 s57, s57, s59
	s_mov_b32 m0, s57
	ds_read_b128 v[162:165], v237 offset:16384
	ds_read_b128 v[166:169], v237 offset:17408
	ds_read_b128 v[184:187], v237 offset:18432
	ds_read_b128 v[188:191], v237 offset:19456
	ds_read_b128 v[192:195], v237 offset:20480
	ds_read_b128 v[196:199], v237 offset:21504
	ds_read_b128 v[200:203], v237 offset:22528
	ds_read_b128 v[214:217], v237 offset:23552
	global_load_lds_dwordx4 v0, vcc
	s_add_i32 m0, s57, 0x2000
	s_add_i32 s45, s45, s59
	global_load_lds_dwordx4 v176, vcc
	s_mov_b32 m0, s45
	s_nop 0
	global_load_lds_dwordx4 v242, vcc
	s_add_i32 m0, s45, 0x2000
	s_nop 0
	global_load_lds_dwordx4 v249, vcc
	s_mov_b32 m0, s70
	s_nop 0
	global_load_lds_dwordx4 v172, s[14:15]
	s_mov_b32 m0, s4
	s_nop 0
	global_load_lds_dwordx4 v174, s[14:15]
	s_waitcnt vmcnt(8)
	s_waitcnt lgkmcnt(0)
	s_barrier
	s_setprio 1
	v_mfma_f32_16x16x32_bf16 v[58:61], v[130:133], v[162:165], 0
	v_mfma_f32_16x16x32_bf16 v[62:65], v[138:141], v[162:165], 0
	v_mfma_f32_16x16x32_bf16 v[42:45], v[130:133], v[184:187], 0
	v_mfma_f32_16x16x32_bf16 v[46:49], v[138:141], v[184:187], 0
	v_mfma_f32_16x16x32_bf16 v[26:29], v[130:133], v[192:195], 0
	v_mfma_f32_16x16x32_bf16 v[30:33], v[138:141], v[192:195], 0
	v_mfma_f32_16x16x32_bf16 v[10:13], v[130:133], v[200:203], 0
	v_mfma_f32_16x16x32_bf16 v[14:17], v[138:141], v[200:203], 0
	v_mfma_f32_16x16x32_bf16 v[58:61], v[134:137], v[166:169], v[58:61]
	v_mfma_f32_16x16x32_bf16 v[62:65], v[142:145], v[166:169], v[62:65]
	v_mfma_f32_16x16x32_bf16 v[42:45], v[134:137], v[188:191], v[42:45]
	v_mfma_f32_16x16x32_bf16 v[46:49], v[142:145], v[188:191], v[46:49]
	v_mfma_f32_16x16x32_bf16 v[26:29], v[134:137], v[196:199], v[26:29]
	v_mfma_f32_16x16x32_bf16 v[30:33], v[142:145], v[196:199], v[30:33]
	v_mfma_f32_16x16x32_bf16 v[10:13], v[134:137], v[214:217], v[10:13]
	v_mfma_f32_16x16x32_bf16 v[14:17], v[142:145], v[214:217], v[14:17]
	v_mfma_f32_16x16x32_bf16 v[50:53], v[146:149], v[162:165], 0
	v_mfma_f32_16x16x32_bf16 v[54:57], v[154:157], v[162:165], 0
	v_mfma_f32_16x16x32_bf16 v[34:37], v[146:149], v[184:187], 0
	v_mfma_f32_16x16x32_bf16 v[38:41], v[154:157], v[184:187], 0
	v_mfma_f32_16x16x32_bf16 v[18:21], v[146:149], v[192:195], 0
	v_mfma_f32_16x16x32_bf16 v[22:25], v[154:157], v[192:195], 0
	v_mfma_f32_16x16x32_bf16 v[6:9], v[146:149], v[200:203], 0
	v_mfma_f32_16x16x32_bf16 v[2:5], v[154:157], v[200:203], 0
	v_mfma_f32_16x16x32_bf16 v[50:53], v[150:153], v[166:169], v[50:53]
	v_mfma_f32_16x16x32_bf16 v[54:57], v[158:161], v[166:169], v[54:57]
	v_mfma_f32_16x16x32_bf16 v[34:37], v[150:153], v[188:191], v[34:37]
	v_mfma_f32_16x16x32_bf16 v[38:41], v[158:161], v[188:191], v[38:41]
	v_mfma_f32_16x16x32_bf16 v[18:21], v[150:153], v[196:199], v[18:21]
	v_mfma_f32_16x16x32_bf16 v[22:25], v[158:161], v[196:199], v[22:25]
	v_mfma_f32_16x16x32_bf16 v[6:9], v[150:153], v[214:217], v[6:9]
	v_mfma_f32_16x16x32_bf16 v[2:5], v[158:161], v[214:217], v[2:5]
	s_setprio 0
	s_barrier
	s_add_i32 s45, 0, 0x18000
	s_add_i32 s57, 0, 0x1c000
	ds_read_b128 v[130:133], v248 offset:32768
	ds_read_b128 v[134:137], v248 offset:33792
	ds_read_b128 v[138:141], v248 offset:34816
	ds_read_b128 v[142:145], v248 offset:35840
	ds_read_b128 v[146:149], v248 offset:49152
	ds_read_b128 v[150:153], v248 offset:50176
	ds_read_b128 v[154:157], v248 offset:51200
	ds_read_b128 v[158:161], v248 offset:52224
	s_mov_b32 m0, s63
	ds_read_b128 v[162:165], v237 offset:32768
	ds_read_b128 v[166:169], v237 offset:33792
	ds_read_b128 v[184:187], v237 offset:34816
	ds_read_b128 v[188:191], v237 offset:35840
	ds_read_b128 v[192:195], v237 offset:36864
	ds_read_b128 v[196:199], v237 offset:37888
	ds_read_b128 v[200:203], v237 offset:38912
	ds_read_b128 v[214:217], v237 offset:39936
	global_load_lds_dwordx4 v180, s[14:15]
	s_mov_b32 m0, s68
	s_nop 0
	global_load_lds_dwordx4 v182, s[14:15]
	s_waitcnt vmcnt(8)
	s_waitcnt lgkmcnt(0)
	s_barrier
	s_setprio 1
	v_mfma_f32_16x16x32_bf16 v[122:125], v[130:133], v[162:165], v[122:125]
	v_mfma_f32_16x16x32_bf16 v[126:129], v[138:141], v[162:165], v[126:129]
	v_mfma_f32_16x16x32_bf16 v[106:109], v[130:133], v[184:187], v[106:109]
	v_mfma_f32_16x16x32_bf16 v[110:113], v[138:141], v[184:187], v[110:113]
	v_mfma_f32_16x16x32_bf16 v[90:93], v[130:133], v[192:195], v[90:93]
	v_mfma_f32_16x16x32_bf16 v[94:97], v[138:141], v[192:195], v[94:97]
	v_mfma_f32_16x16x32_bf16 v[74:77], v[130:133], v[200:203], v[74:77]
	v_mfma_f32_16x16x32_bf16 v[78:81], v[138:141], v[200:203], v[78:81]
	v_mfma_f32_16x16x32_bf16 v[122:125], v[134:137], v[166:169], v[122:125]
	v_mfma_f32_16x16x32_bf16 v[126:129], v[142:145], v[166:169], v[126:129]
	v_mfma_f32_16x16x32_bf16 v[106:109], v[134:137], v[188:191], v[106:109]
	v_mfma_f32_16x16x32_bf16 v[110:113], v[142:145], v[188:191], v[110:113]
	v_mfma_f32_16x16x32_bf16 v[90:93], v[134:137], v[196:199], v[90:93]
	v_mfma_f32_16x16x32_bf16 v[94:97], v[142:145], v[196:199], v[94:97]
	v_mfma_f32_16x16x32_bf16 v[74:77], v[134:137], v[214:217], v[74:77]
	v_mfma_f32_16x16x32_bf16 v[78:81], v[142:145], v[214:217], v[78:81]
	v_mfma_f32_16x16x32_bf16 v[114:117], v[146:149], v[162:165], v[114:117]
	v_mfma_f32_16x16x32_bf16 v[118:121], v[154:157], v[162:165], v[118:121]
	v_mfma_f32_16x16x32_bf16 v[98:101], v[146:149], v[184:187], v[98:101]
	v_mfma_f32_16x16x32_bf16 v[102:105], v[154:157], v[184:187], v[102:105]
	v_mfma_f32_16x16x32_bf16 v[82:85], v[146:149], v[192:195], v[82:85]
	v_mfma_f32_16x16x32_bf16 v[86:89], v[154:157], v[192:195], v[86:89]
	v_mfma_f32_16x16x32_bf16 v[66:69], v[146:149], v[200:203], v[66:69]
	v_mfma_f32_16x16x32_bf16 v[70:73], v[154:157], v[200:203], v[70:73]
	v_mfma_f32_16x16x32_bf16 v[114:117], v[150:153], v[166:169], v[114:117]
	v_mfma_f32_16x16x32_bf16 v[118:121], v[158:161], v[166:169], v[118:121]
	v_mfma_f32_16x16x32_bf16 v[98:101], v[150:153], v[188:191], v[98:101]
	v_mfma_f32_16x16x32_bf16 v[102:105], v[158:161], v[188:191], v[102:105]
	v_mfma_f32_16x16x32_bf16 v[82:85], v[150:153], v[196:199], v[82:85]
	v_mfma_f32_16x16x32_bf16 v[86:89], v[158:161], v[196:199], v[86:89]
	v_mfma_f32_16x16x32_bf16 v[66:69], v[150:153], v[214:217], v[66:69]
	v_mfma_f32_16x16x32_bf16 v[70:73], v[158:161], v[214:217], v[70:73]
	s_setprio 0
	s_barrier
	s_add_i32 m0, s45, s59
	ds_read_b128 v[162:165], v237 offset:49152
	ds_read_b128 v[166:169], v237 offset:50176
	ds_read_b128 v[184:187], v237 offset:51200
	ds_read_b128 v[188:191], v237 offset:52224
	ds_read_b128 v[192:195], v237 offset:53248
	ds_read_b128 v[196:199], v237 offset:54272
	ds_read_b128 v[200:203], v237 offset:55296
	ds_read_b128 v[214:217], v237 offset:56320
	global_load_lds_dwordx4 v204, vcc
	s_add_i32 m0, m0, 0x2000
	s_nop 0
	global_load_lds_dwordx4 v205, vcc
	s_add_i32 m0, s57, s59
	s_nop 0
	global_load_lds_dwordx4 v218, vcc
	s_add_i32 m0, m0, 0x2000
	s_nop 0
	global_load_lds_dwordx4 v219, vcc
	s_mov_b32 m0, s67
	s_nop 0
	global_load_lds_dwordx4 v220, s[14:15]
	s_mov_b32 m0, s7
	s_nop 0
	global_load_lds_dwordx4 v221, s[14:15]
	s_waitcnt vmcnt(8)
	s_waitcnt lgkmcnt(0)
	s_barrier
	s_setprio 1
	v_mfma_f32_16x16x32_bf16 v[58:61], v[130:133], v[162:165], v[58:61]
	v_mfma_f32_16x16x32_bf16 v[62:65], v[138:141], v[162:165], v[62:65]
	v_mfma_f32_16x16x32_bf16 v[42:45], v[130:133], v[184:187], v[42:45]
	v_mfma_f32_16x16x32_bf16 v[46:49], v[138:141], v[184:187], v[46:49]
	v_mfma_f32_16x16x32_bf16 v[26:29], v[130:133], v[192:195], v[26:29]
	v_mfma_f32_16x16x32_bf16 v[30:33], v[138:141], v[192:195], v[30:33]
	v_mfma_f32_16x16x32_bf16 v[10:13], v[130:133], v[200:203], v[10:13]
	v_mfma_f32_16x16x32_bf16 v[14:17], v[138:141], v[200:203], v[14:17]
	v_mfma_f32_16x16x32_bf16 v[58:61], v[134:137], v[166:169], v[58:61]
	v_mfma_f32_16x16x32_bf16 v[62:65], v[142:145], v[166:169], v[62:65]
	v_mfma_f32_16x16x32_bf16 v[42:45], v[134:137], v[188:191], v[42:45]
	v_mfma_f32_16x16x32_bf16 v[46:49], v[142:145], v[188:191], v[46:49]
	v_mfma_f32_16x16x32_bf16 v[26:29], v[134:137], v[196:199], v[26:29]
	v_mfma_f32_16x16x32_bf16 v[30:33], v[142:145], v[196:199], v[30:33]
	v_mfma_f32_16x16x32_bf16 v[10:13], v[134:137], v[214:217], v[10:13]
	v_mfma_f32_16x16x32_bf16 v[14:17], v[142:145], v[214:217], v[14:17]
	v_mfma_f32_16x16x32_bf16 v[50:53], v[146:149], v[162:165], v[50:53]
	v_mfma_f32_16x16x32_bf16 v[54:57], v[154:157], v[162:165], v[54:57]
	v_mfma_f32_16x16x32_bf16 v[34:37], v[146:149], v[184:187], v[34:37]
	v_mfma_f32_16x16x32_bf16 v[38:41], v[154:157], v[184:187], v[38:41]
	v_mfma_f32_16x16x32_bf16 v[18:21], v[146:149], v[192:195], v[18:21]
	v_mfma_f32_16x16x32_bf16 v[22:25], v[154:157], v[192:195], v[22:25]
	v_mfma_f32_16x16x32_bf16 v[6:9], v[146:149], v[200:203], v[6:9]
	v_mfma_f32_16x16x32_bf16 v[2:5], v[154:157], v[200:203], v[2:5]
	v_mfma_f32_16x16x32_bf16 v[50:53], v[150:153], v[166:169], v[50:53]
	v_mfma_f32_16x16x32_bf16 v[54:57], v[158:161], v[166:169], v[54:57]
	v_mfma_f32_16x16x32_bf16 v[34:37], v[150:153], v[188:191], v[34:37]
	v_mfma_f32_16x16x32_bf16 v[38:41], v[158:161], v[188:191], v[38:41]
	v_mfma_f32_16x16x32_bf16 v[18:21], v[150:153], v[196:199], v[18:21]
	v_mfma_f32_16x16x32_bf16 v[22:25], v[158:161], v[196:199], v[22:25]
	v_mfma_f32_16x16x32_bf16 v[6:9], v[150:153], v[214:217], v[6:9]
	v_mfma_f32_16x16x32_bf16 v[2:5], v[158:161], v[214:217], v[2:5]
	s_setprio 0
	s_barrier
	s_add_u32 s0, s0, 0x100
	s_addc_u32 s1, s1, 0
	s_add_u32 s42, s42, 0x100
	s_addc_u32 s43, s43, 0
	s_cmp_ge_u32 s44, s61
	s_mov_b32 s14, s44
	s_cbranch_scc1 .Lk_exit
.LBB0_178:
	s_add_i32 s44, s14, 2
	s_add_u32 s45, s0, 0x80
	s_addc_u32 s15, s1, 0
	s_add_i32 s57, 0, 0x10000
	s_cmp_eq_u32 s18, s14
	s_cselect_b32 s15, s89, s15
	s_cselect_b32 s14, s88, s45
	s_cselect_b32 vcc_hi, s11, s43
	s_cselect_b32 vcc_lo, s10, s42
	s_add_i32 s45, 0, 0x14000
	s_waitcnt lgkmcnt(0)
	ds_read_b128 v[130:133], v248
	ds_read_b128 v[134:137], v248 offset:1024
	ds_read_b128 v[138:141], v248 offset:2048
	ds_read_b128 v[142:145], v248 offset:3072
	ds_read_b128 v[146:149], v248 offset:16384
	ds_read_b128 v[150:153], v248 offset:17408
	ds_read_b128 v[154:157], v248 offset:18432
	ds_read_b128 v[158:161], v248 offset:19456
	s_add_i32 m0, s70, 0xc000
	ds_read_b128 v[162:165], v237
	ds_read_b128 v[166:169], v237 offset:1024
	ds_read_b128 v[184:187], v237 offset:2048
	ds_read_b128 v[188:191], v237 offset:3072
	ds_read_b128 v[192:195], v237 offset:4096
	ds_read_b128 v[196:199], v237 offset:5120
	ds_read_b128 v[200:203], v237 offset:6144
	ds_read_b128 v[214:217], v237 offset:7168
	global_load_lds_dwordx4 v180, s[0:1]
	s_add_i32 m0, s70, 0xe000
	s_nop 0
	global_load_lds_dwordx4 v182, s[0:1]
	s_waitcnt vmcnt(8)
	s_waitcnt lgkmcnt(0)
	s_barrier
	s_setprio 1
	v_mfma_f32_16x16x32_bf16 v[122:125], v[130:133], v[162:165], v[122:125]
	v_mfma_f32_16x16x32_bf16 v[126:129], v[138:141], v[162:165], v[126:129]
	v_mfma_f32_16x16x32_bf16 v[106:109], v[130:133], v[184:187], v[106:109]
	v_mfma_f32_16x16x32_bf16 v[110:113], v[138:141], v[184:187], v[110:113]
	v_mfma_f32_16x16x32_bf16 v[90:93], v[130:133], v[192:195], v[90:93]
	v_mfma_f32_16x16x32_bf16 v[94:97], v[138:141], v[192:195], v[94:97]
	v_mfma_f32_16x16x32_bf16 v[74:77], v[130:133], v[200:203], v[74:77]
	v_mfma_f32_16x16x32_bf16 v[78:81], v[138:141], v[200:203], v[78:81]
	v_mfma_f32_16x16x32_bf16 v[122:125], v[134:137], v[166:169], v[122:125]
	v_mfma_f32_16x16x32_bf16 v[126:129], v[142:145], v[166:169], v[126:129]
	v_mfma_f32_16x16x32_bf16 v[106:109], v[134:137], v[188:191], v[106:109]
	v_mfma_f32_16x16x32_bf16 v[110:113], v[142:145], v[188:191], v[110:113]
	v_mfma_f32_16x16x32_bf16 v[90:93], v[134:137], v[196:199], v[90:93]
	v_mfma_f32_16x16x32_bf16 v[94:97], v[142:145], v[196:199], v[94:97]
	v_mfma_f32_16x16x32_bf16 v[74:77], v[134:137], v[214:217], v[74:77]
	v_mfma_f32_16x16x32_bf16 v[78:81], v[142:145], v[214:217], v[78:81]
	v_mfma_f32_16x16x32_bf16 v[114:117], v[146:149], v[162:165], v[114:117]
	v_mfma_f32_16x16x32_bf16 v[118:121], v[154:157], v[162:165], v[118:121]
	v_mfma_f32_16x16x32_bf16 v[98:101], v[146:149], v[184:187], v[98:101]
	v_mfma_f32_16x16x32_bf16 v[102:105], v[154:157], v[184:187], v[102:105]
	v_mfma_f32_16x16x32_bf16 v[82:85], v[146:149], v[192:195], v[82:85]
	v_mfma_f32_16x16x32_bf16 v[86:89], v[154:157], v[192:195], v[86:89]
	v_mfma_f32_16x16x32_bf16 v[66:69], v[146:149], v[200:203], v[66:69]
	v_mfma_f32_16x16x32_bf16 v[70:73], v[154:157], v[200:203], v[70:73]
	v_mfma_f32_16x16x32_bf16 v[114:117], v[150:153], v[166:169], v[114:117]
	v_mfma_f32_16x16x32_bf16 v[118:121], v[158:161], v[166:169], v[118:121]
	v_mfma_f32_16x16x32_bf16 v[98:101], v[150:153], v[188:191], v[98:101]
	v_mfma_f32_16x16x32_bf16 v[102:105], v[158:161], v[188:191], v[102:105]
	v_mfma_f32_16x16x32_bf16 v[82:85], v[150:153], v[196:199], v[82:85]
	v_mfma_f32_16x16x32_bf16 v[86:89], v[158:161], v[196:199], v[86:89]
	v_mfma_f32_16x16x32_bf16 v[66:69], v[150:153], v[214:217], v[66:69]
	v_mfma_f32_16x16x32_bf16 v[70:73], v[158:161], v[214:217], v[70:73]
	s_setprio 0
	s_barrier
	s_add_i32 s57, s57, s59
	s_mov_b32 m0, s57
	ds_read_b128 v[162:165], v237 offset:16384
	ds_read_b128 v[166:169], v237 offset:17408
	ds_read_b128 v[184:187], v237 offset:18432
	ds_read_b128 v[188:191], v237 offset:19456
	ds_read_b128 v[192:195], v237 offset:20480
	ds_read_b128 v[196:199], v237 offset:21504
	ds_read_b128 v[200:203], v237 offset:22528
	ds_read_b128 v[214:217], v237 offset:23552
	global_load_lds_dwordx4 v0, vcc
	s_add_i32 m0, s57, 0x2000
	s_add_i32 s45, s45, s59
	global_load_lds_dwordx4 v176, vcc
	s_mov_b32 m0, s45
	s_nop 0
	global_load_lds_dwordx4 v242, vcc
	s_add_i32 m0, s45, 0x2000
	s_nop 0
	global_load_lds_dwordx4 v249, vcc
	s_mov_b32 m0, s70
	s_nop 0
	global_load_lds_dwordx4 v172, s[14:15]
	s_mov_b32 m0, s4
	s_nop 0
	global_load_lds_dwordx4 v174, s[14:15]
	s_waitcnt vmcnt(8)
	s_waitcnt lgkmcnt(0)
	s_barrier
	s_setprio 1
	v_mfma_f32_16x16x32_bf16 v[58:61], v[130:133], v[162:165], v[58:61]
	v_mfma_f32_16x16x32_bf16 v[62:65], v[138:141], v[162:165], v[62:65]
	v_mfma_f32_16x16x32_bf16 v[42:45], v[130:133], v[184:187], v[42:45]
	v_mfma_f32_16x16x32_bf16 v[46:49], v[138:141], v[184:187], v[46:49]
	v_mfma_f32_16x16x32_bf16 v[26:29], v[130:133], v[192:195], v[26:29]
	v_mfma_f32_16x16x32_bf16 v[30:33], v[138:141], v[192:195], v[30:33]
	v_mfma_f32_16x16x32_bf16 v[10:13], v[130:133], v[200:203], v[10:13]
	v_mfma_f32_16x16x32_bf16 v[14:17], v[138:141], v[200:203], v[14:17]
	v_mfma_f32_16x16x32_bf16 v[58:61], v[134:137], v[166:169], v[58:61]
	v_mfma_f32_16x16x32_bf16 v[62:65], v[142:145], v[166:169], v[62:65]
	v_mfma_f32_16x16x32_bf16 v[42:45], v[134:137], v[188:191], v[42:45]
	v_mfma_f32_16x16x32_bf16 v[46:49], v[142:145], v[188:191], v[46:49]
	v_mfma_f32_16x16x32_bf16 v[26:29], v[134:137], v[196:199], v[26:29]
	v_mfma_f32_16x16x32_bf16 v[30:33], v[142:145], v[196:199], v[30:33]
	v_mfma_f32_16x16x32_bf16 v[10:13], v[134:137], v[214:217], v[10:13]
	v_mfma_f32_16x16x32_bf16 v[14:17], v[142:145], v[214:217], v[14:17]
	v_mfma_f32_16x16x32_bf16 v[50:53], v[146:149], v[162:165], v[50:53]
	v_mfma_f32_16x16x32_bf16 v[54:57], v[154:157], v[162:165], v[54:57]
	v_mfma_f32_16x16x32_bf16 v[34:37], v[146:149], v[184:187], v[34:37]
	v_mfma_f32_16x16x32_bf16 v[38:41], v[154:157], v[184:187], v[38:41]
	v_mfma_f32_16x16x32_bf16 v[18:21], v[146:149], v[192:195], v[18:21]
	v_mfma_f32_16x16x32_bf16 v[22:25], v[154:157], v[192:195], v[22:25]
	v_mfma_f32_16x16x32_bf16 v[6:9], v[146:149], v[200:203], v[6:9]
	v_mfma_f32_16x16x32_bf16 v[2:5], v[154:157], v[200:203], v[2:5]
	v_mfma_f32_16x16x32_bf16 v[50:53], v[150:153], v[166:169], v[50:53]
	v_mfma_f32_16x16x32_bf16 v[54:57], v[158:161], v[166:169], v[54:57]
	v_mfma_f32_16x16x32_bf16 v[34:37], v[150:153], v[188:191], v[34:37]
	v_mfma_f32_16x16x32_bf16 v[38:41], v[158:161], v[188:191], v[38:41]
	v_mfma_f32_16x16x32_bf16 v[18:21], v[150:153], v[196:199], v[18:21]
	v_mfma_f32_16x16x32_bf16 v[22:25], v[158:161], v[196:199], v[22:25]
	v_mfma_f32_16x16x32_bf16 v[6:9], v[150:153], v[214:217], v[6:9]
	v_mfma_f32_16x16x32_bf16 v[2:5], v[158:161], v[214:217], v[2:5]
	s_setprio 0
	s_barrier
	s_add_i32 s45, 0, 0x18000
	s_add_i32 s57, 0, 0x1c000
	ds_read_b128 v[130:133], v248 offset:32768
	ds_read_b128 v[134:137], v248 offset:33792
	ds_read_b128 v[138:141], v248 offset:34816
	ds_read_b128 v[142:145], v248 offset:35840
	ds_read_b128 v[146:149], v248 offset:49152
	ds_read_b128 v[150:153], v248 offset:50176
	ds_read_b128 v[154:157], v248 offset:51200
	ds_read_b128 v[158:161], v248 offset:52224
	s_mov_b32 m0, s63
	ds_read_b128 v[162:165], v237 offset:32768
	ds_read_b128 v[166:169], v237 offset:33792
	ds_read_b128 v[184:187], v237 offset:34816
	ds_read_b128 v[188:191], v237 offset:35840
	ds_read_b128 v[192:195], v237 offset:36864
	ds_read_b128 v[196:199], v237 offset:37888
	ds_read_b128 v[200:203], v237 offset:38912
	ds_read_b128 v[214:217], v237 offset:39936
	global_load_lds_dwordx4 v180, s[14:15]
	s_mov_b32 m0, s68
	s_nop 0
	global_load_lds_dwordx4 v182, s[14:15]
	s_waitcnt vmcnt(8)
	s_waitcnt lgkmcnt(0)
	s_barrier
	s_setprio 1
	v_mfma_f32_16x16x32_bf16 v[122:125], v[130:133], v[162:165], v[122:125]
	v_mfma_f32_16x16x32_bf16 v[126:129], v[138:141], v[162:165], v[126:129]
	v_mfma_f32_16x16x32_bf16 v[106:109], v[130:133], v[184:187], v[106:109]
	v_mfma_f32_16x16x32_bf16 v[110:113], v[138:141], v[184:187], v[110:113]
	v_mfma_f32_16x16x32_bf16 v[90:93], v[130:133], v[192:195], v[90:93]
	v_mfma_f32_16x16x32_bf16 v[94:97], v[138:141], v[192:195], v[94:97]
	v_mfma_f32_16x16x32_bf16 v[74:77], v[130:133], v[200:203], v[74:77]
	v_mfma_f32_16x16x32_bf16 v[78:81], v[138:141], v[200:203], v[78:81]
	v_mfma_f32_16x16x32_bf16 v[122:125], v[134:137], v[166:169], v[122:125]
	v_mfma_f32_16x16x32_bf16 v[126:129], v[142:145], v[166:169], v[126:129]
	v_mfma_f32_16x16x32_bf16 v[106:109], v[134:137], v[188:191], v[106:109]
	v_mfma_f32_16x16x32_bf16 v[110:113], v[142:145], v[188:191], v[110:113]
	v_mfma_f32_16x16x32_bf16 v[90:93], v[134:137], v[196:199], v[90:93]
	v_mfma_f32_16x16x32_bf16 v[94:97], v[142:145], v[196:199], v[94:97]
	v_mfma_f32_16x16x32_bf16 v[74:77], v[134:137], v[214:217], v[74:77]
	v_mfma_f32_16x16x32_bf16 v[78:81], v[142:145], v[214:217], v[78:81]
	v_mfma_f32_16x16x32_bf16 v[114:117], v[146:149], v[162:165], v[114:117]
	v_mfma_f32_16x16x32_bf16 v[118:121], v[154:157], v[162:165], v[118:121]
	v_mfma_f32_16x16x32_bf16 v[98:101], v[146:149], v[184:187], v[98:101]
	v_mfma_f32_16x16x32_bf16 v[102:105], v[154:157], v[184:187], v[102:105]
	v_mfma_f32_16x16x32_bf16 v[82:85], v[146:149], v[192:195], v[82:85]
	v_mfma_f32_16x16x32_bf16 v[86:89], v[154:157], v[192:195], v[86:89]
	v_mfma_f32_16x16x32_bf16 v[66:69], v[146:149], v[200:203], v[66:69]
	v_mfma_f32_16x16x32_bf16 v[70:73], v[154:157], v[200:203], v[70:73]
	v_mfma_f32_16x16x32_bf16 v[114:117], v[150:153], v[166:169], v[114:117]
	v_mfma_f32_16x16x32_bf16 v[118:121], v[158:161], v[166:169], v[118:121]
	v_mfma_f32_16x16x32_bf16 v[98:101], v[150:153], v[188:191], v[98:101]
	v_mfma_f32_16x16x32_bf16 v[102:105], v[158:161], v[188:191], v[102:105]
	v_mfma_f32_16x16x32_bf16 v[82:85], v[150:153], v[196:199], v[82:85]
	v_mfma_f32_16x16x32_bf16 v[86:89], v[158:161], v[196:199], v[86:89]
	v_mfma_f32_16x16x32_bf16 v[66:69], v[150:153], v[214:217], v[66:69]
	v_mfma_f32_16x16x32_bf16 v[70:73], v[158:161], v[214:217], v[70:73]
	s_setprio 0
	s_barrier
	s_add_i32 m0, s45, s59
	ds_read_b128 v[162:165], v237 offset:49152
	ds_read_b128 v[166:169], v237 offset:50176
	ds_read_b128 v[184:187], v237 offset:51200
	ds_read_b128 v[188:191], v237 offset:52224
	ds_read_b128 v[192:195], v237 offset:53248
	ds_read_b128 v[196:199], v237 offset:54272
	ds_read_b128 v[200:203], v237 offset:55296
	ds_read_b128 v[214:217], v237 offset:56320
	global_load_lds_dwordx4 v204, vcc
	s_add_i32 m0, m0, 0x2000
	s_nop 0
	global_load_lds_dwordx4 v205, vcc
	s_add_i32 m0, s57, s59
	s_nop 0
	global_load_lds_dwordx4 v218, vcc
	s_add_i32 m0, m0, 0x2000
	s_nop 0
	global_load_lds_dwordx4 v219, vcc
	s_mov_b32 m0, s67
	s_nop 0
	global_load_lds_dwordx4 v220, s[14:15]
	s_mov_b32 m0, s7
	s_nop 0
	global_load_lds_dwordx4 v221, s[14:15]
	s_waitcnt vmcnt(8)
	s_waitcnt lgkmcnt(0)
	s_barrier
	s_setprio 1
	v_mfma_f32_16x16x32_bf16 v[58:61], v[130:133], v[162:165], v[58:61]
	v_mfma_f32_16x16x32_bf16 v[62:65], v[138:141], v[162:165], v[62:65]
	v_mfma_f32_16x16x32_bf16 v[42:45], v[130:133], v[184:187], v[42:45]
	v_mfma_f32_16x16x32_bf16 v[46:49], v[138:141], v[184:187], v[46:49]
	v_mfma_f32_16x16x32_bf16 v[26:29], v[130:133], v[192:195], v[26:29]
	v_mfma_f32_16x16x32_bf16 v[30:33], v[138:141], v[192:195], v[30:33]
	v_mfma_f32_16x16x32_bf16 v[10:13], v[130:133], v[200:203], v[10:13]
	v_mfma_f32_16x16x32_bf16 v[14:17], v[138:141], v[200:203], v[14:17]
	v_mfma_f32_16x16x32_bf16 v[58:61], v[134:137], v[166:169], v[58:61]
	v_mfma_f32_16x16x32_bf16 v[62:65], v[142:145], v[166:169], v[62:65]
	v_mfma_f32_16x16x32_bf16 v[42:45], v[134:137], v[188:191], v[42:45]
	v_mfma_f32_16x16x32_bf16 v[46:49], v[142:145], v[188:191], v[46:49]
	v_mfma_f32_16x16x32_bf16 v[26:29], v[134:137], v[196:199], v[26:29]
	v_mfma_f32_16x16x32_bf16 v[30:33], v[142:145], v[196:199], v[30:33]
	v_mfma_f32_16x16x32_bf16 v[10:13], v[134:137], v[214:217], v[10:13]
	v_mfma_f32_16x16x32_bf16 v[14:17], v[142:145], v[214:217], v[14:17]
	v_mfma_f32_16x16x32_bf16 v[50:53], v[146:149], v[162:165], v[50:53]
	v_mfma_f32_16x16x32_bf16 v[54:57], v[154:157], v[162:165], v[54:57]
	v_mfma_f32_16x16x32_bf16 v[34:37], v[146:149], v[184:187], v[34:37]
	v_mfma_f32_16x16x32_bf16 v[38:41], v[154:157], v[184:187], v[38:41]
	v_mfma_f32_16x16x32_bf16 v[18:21], v[146:149], v[192:195], v[18:21]
	v_mfma_f32_16x16x32_bf16 v[22:25], v[154:157], v[192:195], v[22:25]
	v_mfma_f32_16x16x32_bf16 v[6:9], v[146:149], v[200:203], v[6:9]
	v_mfma_f32_16x16x32_bf16 v[2:5], v[154:157], v[200:203], v[2:5]
	v_mfma_f32_16x16x32_bf16 v[50:53], v[150:153], v[166:169], v[50:53]
	v_mfma_f32_16x16x32_bf16 v[54:57], v[158:161], v[166:169], v[54:57]
	v_mfma_f32_16x16x32_bf16 v[34:37], v[150:153], v[188:191], v[34:37]
	v_mfma_f32_16x16x32_bf16 v[38:41], v[158:161], v[188:191], v[38:41]
	v_mfma_f32_16x16x32_bf16 v[18:21], v[150:153], v[196:199], v[18:21]
	v_mfma_f32_16x16x32_bf16 v[22:25], v[158:161], v[196:199], v[22:25]
	v_mfma_f32_16x16x32_bf16 v[6:9], v[150:153], v[214:217], v[6:9]
	v_mfma_f32_16x16x32_bf16 v[2:5], v[158:161], v[214:217], v[2:5]
	s_setprio 0
	s_barrier
	s_add_u32 s0, s0, 0x100
	s_addc_u32 s1, s1, 0
	s_add_u32 s42, s42, 0x100
	s_addc_u32 s43, s43, 0
	s_cmp_ge_u32 s44, s61
	s_mov_b32 s14, s44
	s_cbranch_scc0 .LBB0_178
